# v33
# speedup vs baseline: 1.0052x; 1.0025x over previous
; DEVI void attn_unit(const Params& p, char* lds, int au) {
;     ...
;     if (typeB && i > 0) PVSTEP(lds + 32768 + vprev * 16384);
.LBB0_209:
	s_lshl_b32 s3, s15, 14
	s_addk_i32 s3, 0xc000
	s_cmp_lg_u32 s15, 0
	s_cselect_b32 s3, s3, 0x8000
	v_or_b32_e32 v94, s3, v185
	v_add_u32_e32 v162, v94, v183
	v_add_u32_e32 v163, v94, v184
	ds_read_b128 v[94:97], v162 offset:32768
	ds_read_b128 v[106:109], v162 offset:34816
	ds_read_b128 v[146:149], v162 offset:36864
	ds_read_b128 v[150:153], v162 offset:38912
	ds_read_b128 v[114:117], v163 offset:32768
	ds_read_b128 v[118:121], v163 offset:34816
	ds_read_b128 v[154:157], v163 offset:36864
	ds_read_b128 v[158:161], v163 offset:38912
	s_waitcnt lgkmcnt(4)
	s_setprio 1
	v_mfma_f32_16x16x32_bf16 v[82:85], v[94:97], v[90:93], v[82:85]
	v_mfma_f32_16x16x32_bf16 v[78:81], v[94:97], v[110:113], v[78:81]
	v_mfma_f32_16x16x32_bf16 v[74:77], v[106:109], v[90:93], v[74:77]
	v_mfma_f32_16x16x32_bf16 v[70:73], v[106:109], v[110:113], v[70:73]
	v_mfma_f32_16x16x32_bf16 v[66:69], v[146:149], v[90:93], v[66:69]
	v_mfma_f32_16x16x32_bf16 v[58:61], v[146:149], v[110:113], v[58:61]
	v_mfma_f32_16x16x32_bf16 v[54:57], v[150:153], v[90:93], v[54:57]
	v_mfma_f32_16x16x32_bf16 v[50:53], v[150:153], v[110:113], v[50:53]
	ds_read_b128 v[94:97], v162 offset:40960
	ds_read_b128 v[106:109], v162 offset:43008
	ds_read_b128 v[146:149], v162 offset:45056
	ds_read_b128 v[150:153], v162 offset:47104
	s_waitcnt lgkmcnt(4)
	v_mfma_f32_16x16x32_bf16 v[82:85], v[114:117], v[98:101], v[82:85]
	v_mfma_f32_16x16x32_bf16 v[78:81], v[114:117], v[102:105], v[78:81]
	v_mfma_f32_16x16x32_bf16 v[74:77], v[118:121], v[98:101], v[74:77]
	v_mfma_f32_16x16x32_bf16 v[70:73], v[118:121], v[102:105], v[70:73]
	v_mfma_f32_16x16x32_bf16 v[66:69], v[154:157], v[98:101], v[66:69]
	v_mfma_f32_16x16x32_bf16 v[58:61], v[154:157], v[102:105], v[58:61]
	v_mfma_f32_16x16x32_bf16 v[54:57], v[158:161], v[98:101], v[54:57]
	v_mfma_f32_16x16x32_bf16 v[50:53], v[158:161], v[102:105], v[50:53]
	ds_read_b128 v[114:117], v163 offset:40960
	ds_read_b128 v[118:121], v163 offset:43008
	ds_read_b128 v[154:157], v163 offset:45056
	ds_read_b128 v[158:161], v163 offset:47104
	s_waitcnt lgkmcnt(4)
	v_mfma_f32_16x16x32_bf16 v[46:49], v[94:97], v[90:93], v[46:49]
	v_mfma_f32_16x16x32_bf16 v[42:45], v[94:97], v[110:113], v[42:45]
	v_mfma_f32_16x16x32_bf16 v[38:41], v[106:109], v[90:93], v[38:41]
	v_mfma_f32_16x16x32_bf16 v[34:37], v[106:109], v[110:113], v[34:37]
	v_mfma_f32_16x16x32_bf16 v[30:33], v[146:149], v[90:93], v[30:33]
	v_mfma_f32_16x16x32_bf16 v[26:29], v[146:149], v[110:113], v[26:29]
	v_mfma_f32_16x16x32_bf16 v[22:25], v[150:153], v[90:93], v[22:25]
	v_mfma_f32_16x16x32_bf16 v[2:5], v[150:153], v[110:113], v[2:5]
	s_waitcnt lgkmcnt(0)
	v_mfma_f32_16x16x32_bf16 v[46:49], v[114:117], v[98:101], v[46:49]
	v_mfma_f32_16x16x32_bf16 v[42:45], v[114:117], v[102:105], v[42:45]
	v_mfma_f32_16x16x32_bf16 v[38:41], v[118:121], v[98:101], v[38:41]
	v_mfma_f32_16x16x32_bf16 v[34:37], v[118:121], v[102:105], v[34:37]
	v_mfma_f32_16x16x32_bf16 v[30:33], v[154:157], v[98:101], v[30:33]
	v_mfma_f32_16x16x32_bf16 v[26:29], v[154:157], v[102:105], v[26:29]
	v_mfma_f32_16x16x32_bf16 v[22:25], v[158:161], v[98:101], v[22:25]
	v_mfma_f32_16x16x32_bf16 v[2:5], v[158:161], v[102:105], v[2:5]
	s_setprio 0
